# v33 content with an 8-byte pad at entry (byte-phase check of the K-loop heads)
# speedup vs baseline: 1.0007x; 1.0001x over previous
; #define LAS __attribute__((address_space(3)))
; __global__ void __launch_bounds__(NTHR, 2) fwd_kernel(Args a) {
;     extern __shared__ __attribute__((aligned(16))) unsigned char lds_raw[];
;     LAS unsigned char* lds = (LAS unsigned char*)lds_raw;
;     cg::grid_group grid = cg::this_grid();
;     if (threadIdx.x < 2) ((volatile LAS unsigned*)(lds + LDS_BARST))[threadIdx.x] = 0u;
;     if (a.ws == nullptr) grid.sync();
_Z10fwd_kernel4Args:
	s_nop 0
	s_nop 0
	s_load_dwordx4 s[80:83], s[0:1], 0x98
	s_load_dword s46, s[0:1], 0xa8
	s_mov_b64 s[90:91], s[0:1]
	s_mov_b32 s62, s2
	s_add_u32 s2, s90, 0xa0
	v_and_b32_e32 v210, 0x3ff, v0
	s_addc_u32 s3, s91, 0
	v_cmp_gt_u32_e32 vcc, 2, v210
	s_and_saveexec_b64 s[0:1], vcc
	v_lshl_add_u32 v1, v210, 2, 0
	v_add_u32_e32 v1, 0x23fc0, v1
	v_mov_b32_e32 v2, 0
	ds_write_b32 v1, v2
	s_or_b64 exec, exec, s[0:1]
	s_waitcnt lgkmcnt(0)
	s_cmp_lg_u64 s[80:81], 0
	s_cbranch_scc1 .LBB0_14
	v_lshrrev_b32_e32 v1, 20, v0
	v_lshrrev_b32_e32 v0, 10, v0
	v_or_b32_e32 v0, v0, v1
	s_movk_i32 s0, 0x3ff
	v_and_or_b32 v0, v0, s0, v210
	v_cmp_eq_u32_e32 vcc, 0, v0
	s_barrier
	s_and_saveexec_b64 s[0:1], vcc
	s_cbranch_execz .LBB0_13
	buffer_wbl2 sc1
	s_load_dwordx2 s[2:3], s[2:3], 0x58
	s_mov_b64 s[4:5], exec
	v_mbcnt_lo_u32_b32 v0, s4, 0
	v_mbcnt_hi_u32_b32 v0, s5, v0
	v_cmp_eq_u32_e32 vcc, 0, v0
	s_waitcnt lgkmcnt(0)
	s_load_dword s8, s[2:3], 0x28
	s_and_saveexec_b64 s[6:7], vcc
	s_cbranch_execz .LBB0_6
	s_bcnt1_i32_b64 s4, s[4:5]
	v_mov_b32_e32 v1, 0
	v_mov_b32_e32 v2, s4
	global_atomic_add v1, v1, v2, s[2:3] offset:32 sc0
